# K-loop static priority for the second wave half, loop kept at its original 64-byte placement
# baseline (speedup 1.0000x reference)
; __device__ __forceinline__ void gemm_phase(LAS unsigned char* lds, const Sched& S, const Epi& E) {
;     ...
;     for (int a = 0; a < 2; ++a)
; #pragma unroll
;         for (int b = 0; b < 2; ++b)
; #pragma unroll
;             for (int m = 0; m < 4; ++m)
; #pragma unroll
;                 for (int n = 0; n < 2; ++n) acc[a][b][m][n] = (f32x4){0.f, 0.f, 0.f, 0.f};
;     ...
;         const bool has_next = S.next(ui + 1, nxt);
;         const char* nA = has_next ? nxt.a : cA; const char* nB = has_next ? nxt.b : cB;
;         const int nlda = has_next ? nxt.lda : lda, nldb = has_next ? nxt.ldb : ldb;
;         const size_t hA = (size_t)HALF * lda * 2;
;         const int nt = cur.nt;
;         const int nt_main = has_next ? nt : nt - 2;
.LBB0_261:
	s_mov_b32 s21, s31
	s_lshl_b64 s[66:67], s[20:21], 8
	s_add_i32 s21, s60, -2
	s_and_b64 s[26:27], s[42:43], exec
	s_cselect_b32 s68, s60, s21
	s_cmp_lt_i32 s68, 1
	s_cbranch_scc1 .LBB0_274
	s_add_u32 vcc_lo, s96, 0x80
	s_addc_u32 vcc_hi, s97, 0
	s_add_u32 s2, s8, 0x100
	s_addc_u32 s72, s9, 0
	v_mad_u64_u32 v[2:3], s[8:9], s20, v235, v[206:207]
	v_mov_b32_e32 v3, v1
	s_waitcnt lgkmcnt(0)
	v_lshl_add_u64 v[130:131], s[66:67], 0, v[2:3]
	v_mad_u64_u32 v[2:3], s[8:9], s20, v236, v[208:209]
	v_mov_b32_e32 v3, v1
	v_lshl_add_u64 v[132:133], s[66:67], 0, v[2:3]
	s_mov_b32 s3, s92
	s_mov_b32 s8, 0
	v_mov_b64_e32 v[2:3], 0
	v_mov_b64_e32 v[4:5], 0
	v_mov_b64_e32 v[6:7], 0
	v_mov_b64_e32 v[8:9], 0
	v_mov_b64_e32 v[10:11], 0
	v_mov_b64_e32 v[12:13], 0
	v_mov_b64_e32 v[14:15], 0
	v_mov_b64_e32 v[16:17], 0
	v_mov_b64_e32 v[18:19], 0
	v_mov_b64_e32 v[20:21], 0
	v_mov_b64_e32 v[22:23], 0
	v_mov_b64_e32 v[24:25], 0
	v_mov_b64_e32 v[26:27], 0
	v_mov_b64_e32 v[28:29], 0
	v_mov_b64_e32 v[30:31], 0
	v_mov_b64_e32 v[32:33], 0
	v_mov_b64_e32 v[34:35], 0
	v_mov_b64_e32 v[36:37], 0
	v_mov_b64_e32 v[38:39], 0
	v_mov_b64_e32 v[40:41], 0
	v_mov_b64_e32 v[42:43], 0
	v_mov_b64_e32 v[44:45], 0
	v_mov_b64_e32 v[46:47], 0
	v_mov_b64_e32 v[48:49], 0
	v_mov_b64_e32 v[50:51], 0
	v_mov_b64_e32 v[52:53], 0
	v_mov_b64_e32 v[54:55], 0
	v_mov_b64_e32 v[56:57], 0
	v_mov_b64_e32 v[58:59], 0
	v_mov_b64_e32 v[60:61], 0
	v_mov_b64_e32 v[62:63], 0
	v_mov_b64_e32 v[64:65], 0
	v_mov_b64_e32 v[66:67], 0
	v_mov_b64_e32 v[68:69], 0
	v_mov_b64_e32 v[70:71], 0
	v_mov_b64_e32 v[72:73], 0
	v_mov_b64_e32 v[74:75], 0
	v_mov_b64_e32 v[76:77], 0
	v_mov_b64_e32 v[78:79], 0
	v_mov_b64_e32 v[80:81], 0
	v_mov_b64_e32 v[82:83], 0
	v_mov_b64_e32 v[84:85], 0
	v_mov_b64_e32 v[86:87], 0
	v_mov_b64_e32 v[88:89], 0
	v_mov_b64_e32 v[90:91], 0
	v_mov_b64_e32 v[92:93], 0
	v_mov_b64_e32 v[94:95], 0
	v_mov_b64_e32 v[96:97], 0
	v_mov_b64_e32 v[98:99], 0
	v_mov_b64_e32 v[100:101], 0
	v_mov_b64_e32 v[102:103], 0
	v_mov_b64_e32 v[104:105], 0
	v_mov_b64_e32 v[106:107], 0
	v_mov_b64_e32 v[108:109], 0
	v_mov_b64_e32 v[110:111], 0
	v_mov_b64_e32 v[112:113], 0
	v_mov_b64_e32 v[114:115], 0
	v_mov_b64_e32 v[116:117], 0
	v_mov_b64_e32 v[118:119], 0
	v_mov_b64_e32 v[120:121], 0
	v_mov_b64_e32 v[122:123], 0
	v_mov_b64_e32 v[124:125], 0
	v_mov_b64_e32 v[126:127], 0
	v_mov_b64_e32 v[128:129], 0
	s_nop 0
	s_nop 0
	s_nop 0
	s_nop 0
	s_nop 0
	s_nop 0
	s_nop 0
	s_nop 0
	s_nop 0
	s_nop 0
	v_readlane_b32 s24, v250, 25
	s_nop 0
	s_cmp_lg_u32 s24, 0
	s_cbranch_scc0 .Lmy_np
	s_setprio 1
